# P0 transpose_w: 8 per-tile global loads issued together instead of one at a time with vmcnt(0) each (on top of mlstmA pipelining)
# speedup vs baseline: 1.0075x; 1.0075x over previous
; DI int otid() { int t = __builtin_amdgcn_workitem_id_x(); asm volatile("" : "+v"(t)); return t; }
; DI u16 f2bf(float x) { return (u16)(pack2(x, 0.f) & 0xffffu); }
; DI void transpose_w(const float* __restrict__ src, u16* __restrict__ dst, int N, int Npad, float* tl) {
;     ...
;   for (int t = blockIdx.x; t < ntiles; t += gridDim.x) {
;     const int kt = t / ntn, nt = t - kt * ntn, k0 = kt * 64, n0 = nt * 64;
;     for (int e = otid(); e < 4096; e += 512) { int r = e >> 6, c = e & 63, n = n0 + c; tl[r * 65 + c] = (n < N) ? src[(size_t)(k0 + r) * N + n] : 0.f; }
;     __syncthreads();
;     for (int e = otid(); e < 4096; e += 512) { int r = e >> 6, c = e & 63; dst[(size_t)(n0 + r) * 1024 + k0 + c] = f2bf(tl[c * 65 + r]); }
;     __syncthreads();
.LBB0_13:
	s_mul_hi_i32 s4, s16, 0x92492493
	s_add_i32 s4, s4, s16
	s_lshr_b32 s5, s4, 31
	s_ashr_i32 s4, s4, 5
	s_add_i32 s4, s4, s5
	s_mul_i32 s5, s4, 0xffffffc8
	s_add_i32 s5, s5, s16
	v_mov_b32_e32 v1, v222
	s_lshl_b32 s6, s4, 6
	s_lshl_b32 s17, s5, 6
	s_nop 0
	v_cmp_gt_i32_e32 vcc, s2, v1
	s_and_saveexec_b64 s[8:9], vcc
	s_cbranch_execz .LBB0_18
	v_and_b32_e32 v2, 63, v1
	v_or_b32_e32 v4, s17, v2
	v_ashrrev_i32_e32 v5, 31, v4
	v_cmp_gt_i32_e32 vcc, s3, v4
	s_waitcnt lgkmcnt(0)
	v_lshl_add_u64 v[4:5], v[4:5], 2, s[60:61]
	v_lshl_add_u32 v2, v2, 2, 0
	s_mov_b64 s[10:11], 0
	v_ashrrev_i32_e32 v6, 6, v1
	v_mov_b32_e32 v56, 0
	v_mov_b32_e32 v57, 0
	v_mov_b32_e32 v58, 0
	v_mov_b32_e32 v59, 0
	v_mov_b32_e32 v60, 0
	v_mov_b32_e32 v61, 0
	v_mov_b32_e32 v62, 0
	v_mov_b32_e32 v63, 0
	s_and_saveexec_b64 s[4:5], vcc
	v_add_u32_e32 v7, s6, v6
	v_mad_i64_i32 v[8:9], s[18:19], v7, s12, v[4:5]
	global_load_dword v56, v[8:9], off
	v_add_u32_e32 v6, 8, v6
	v_add_u32_e32 v7, s6, v6
	v_mad_i64_i32 v[8:9], s[18:19], v7, s12, v[4:5]
	global_load_dword v57, v[8:9], off
	v_add_u32_e32 v6, 8, v6
	v_add_u32_e32 v7, s6, v6
	v_mad_i64_i32 v[8:9], s[18:19], v7, s12, v[4:5]
	global_load_dword v58, v[8:9], off
	v_add_u32_e32 v6, 8, v6
	v_add_u32_e32 v7, s6, v6
	v_mad_i64_i32 v[8:9], s[18:19], v7, s12, v[4:5]
	global_load_dword v59, v[8:9], off
	v_add_u32_e32 v6, 8, v6
	v_add_u32_e32 v7, s6, v6
	v_mad_i64_i32 v[8:9], s[18:19], v7, s12, v[4:5]
	global_load_dword v60, v[8:9], off
	v_add_u32_e32 v6, 8, v6
	v_add_u32_e32 v7, s6, v6
	v_mad_i64_i32 v[8:9], s[18:19], v7, s12, v[4:5]
	global_load_dword v61, v[8:9], off
	v_add_u32_e32 v6, 8, v6
	v_add_u32_e32 v7, s6, v6
	v_mad_i64_i32 v[8:9], s[18:19], v7, s12, v[4:5]
	global_load_dword v62, v[8:9], off
	v_add_u32_e32 v6, 8, v6
	v_add_u32_e32 v7, s6, v6
	v_mad_i64_i32 v[8:9], s[18:19], v7, s12, v[4:5]
	global_load_dword v63, v[8:9], off
	v_add_u32_e32 v6, 8, v6
	s_or_b64 exec, exec, s[4:5]
	v_ashrrev_i32_e32 v6, 6, v1
	v_mad_u64_u32 v[8:9], s[4:5], v6, s13, v[2:3]
	v_mov_b32_e32 v64, v8
	v_add_u32_e32 v6, 8, v6
	v_mad_u64_u32 v[8:9], s[4:5], v6, s13, v[2:3]
	v_mov_b32_e32 v65, v8
	v_add_u32_e32 v6, 8, v6
	v_mad_u64_u32 v[8:9], s[4:5], v6, s13, v[2:3]
	v_mov_b32_e32 v66, v8
	v_add_u32_e32 v6, 8, v6
	v_mad_u64_u32 v[8:9], s[4:5], v6, s13, v[2:3]
	v_mov_b32_e32 v67, v8
	v_add_u32_e32 v6, 8, v6
	v_mad_u64_u32 v[8:9], s[4:5], v6, s13, v[2:3]
	v_mov_b32_e32 v68, v8
	v_add_u32_e32 v6, 8, v6
	v_mad_u64_u32 v[8:9], s[4:5], v6, s13, v[2:3]
	v_mov_b32_e32 v69, v8
	v_add_u32_e32 v6, 8, v6
	v_mad_u64_u32 v[8:9], s[4:5], v6, s13, v[2:3]
	v_mov_b32_e32 v70, v8
	v_add_u32_e32 v6, 8, v6
	v_mad_u64_u32 v[8:9], s[4:5], v6, s13, v[2:3]
	v_mov_b32_e32 v71, v8
	v_add_u32_e32 v6, 8, v6
	s_waitcnt vmcnt(7)
	ds_write_b32 v64, v56
	s_waitcnt vmcnt(6)
	ds_write_b32 v65, v57
	s_waitcnt vmcnt(5)
	ds_write_b32 v66, v58
	s_waitcnt vmcnt(4)
	ds_write_b32 v67, v59
	s_waitcnt vmcnt(3)
	ds_write_b32 v68, v60
	s_waitcnt vmcnt(2)
	ds_write_b32 v69, v61
	s_waitcnt vmcnt(1)
	ds_write_b32 v70, v62
	s_waitcnt vmcnt(0)
	ds_write_b32 v71, v63

; DI int otid() { int t = __builtin_amdgcn_workitem_id_x(); asm volatile("" : "+v"(t)); return t; }
; DI u16 f2bf(float x) { return (u16)(pack2(x, 0.f) & 0xffffu); }
; DI void transpose_w(const float* __restrict__ src, u16* __restrict__ dst, int N, int Npad, float* tl) {
;     ...
;   for (int t = blockIdx.x; t < ntiles; t += gridDim.x) {
;     const int kt = t / ntn, nt = t - kt * ntn, k0 = kt * 64, n0 = nt * 64;
;     for (int e = otid(); e < 4096; e += 512) { int r = e >> 6, c = e & 63, n = n0 + c; tl[r * 65 + c] = (n < N) ? src[(size_t)(k0 + r) * N + n] : 0.f; }
;     __syncthreads();
;     for (int e = otid(); e < 4096; e += 512) { int r = e >> 6, c = e & 63; dst[(size_t)(n0 + r) * 1024 + k0 + c] = f2bf(tl[c * 65 + r]); }
;     __syncthreads();
.LBB0_36:
	s_ashr_i32 s4, s17, 31
	s_lshr_b32 s4, s4, 28
	s_add_i32 s4, s17, s4
	s_ashr_i32 s4, s4, 4
	s_lshl_b32 s8, s4, 6
	s_lshl_b32 s4, s4, 10
	s_lshl_b32 s5, s17, 6
	v_mov_b32_e32 v1, v222
	s_sub_i32 s18, s5, s4
	s_nop 0
	v_cmp_gt_i32_e32 vcc, s2, v1
	s_and_saveexec_b64 s[10:11], vcc
	s_cbranch_execz .LBB0_41
	v_and_b32_e32 v2, 63, v1
	v_or_b32_e32 v4, s18, v2
	v_ashrrev_i32_e32 v5, 31, v4
	v_cmp_gt_i32_e32 vcc, s3, v4
	s_waitcnt lgkmcnt(0)
	v_lshl_add_u64 v[4:5], v[4:5], 2, s[42:43]
	v_lshl_add_u32 v2, v2, 2, 0
	s_mov_b64 s[12:13], 0
	v_ashrrev_i32_e32 v6, 6, v1
	v_mov_b32_e32 v56, 0
	v_mov_b32_e32 v57, 0
	v_mov_b32_e32 v58, 0
	v_mov_b32_e32 v59, 0
	v_mov_b32_e32 v60, 0
	v_mov_b32_e32 v61, 0
	v_mov_b32_e32 v62, 0
	v_mov_b32_e32 v63, 0
	s_and_saveexec_b64 s[4:5], vcc
	v_add_u32_e32 v8, s8, v6
	v_ashrrev_i32_e32 v9, 31, v8
	v_lshlrev_b64 v[8:9], 12, v[8:9]
	v_lshl_add_u64 v[8:9], v[4:5], 0, v[8:9]
	global_load_dword v56, v[8:9], off
	v_add_u32_e32 v6, 8, v6
	v_add_u32_e32 v8, s8, v6
	v_ashrrev_i32_e32 v9, 31, v8
	v_lshlrev_b64 v[8:9], 12, v[8:9]
	v_lshl_add_u64 v[8:9], v[4:5], 0, v[8:9]
	global_load_dword v57, v[8:9], off
	v_add_u32_e32 v6, 8, v6
	v_add_u32_e32 v8, s8, v6
	v_ashrrev_i32_e32 v9, 31, v8
	v_lshlrev_b64 v[8:9], 12, v[8:9]
	v_lshl_add_u64 v[8:9], v[4:5], 0, v[8:9]
	global_load_dword v58, v[8:9], off
	v_add_u32_e32 v6, 8, v6
	v_add_u32_e32 v8, s8, v6
	v_ashrrev_i32_e32 v9, 31, v8
	v_lshlrev_b64 v[8:9], 12, v[8:9]
	v_lshl_add_u64 v[8:9], v[4:5], 0, v[8:9]
	global_load_dword v59, v[8:9], off
	v_add_u32_e32 v6, 8, v6
	v_add_u32_e32 v8, s8, v6
	v_ashrrev_i32_e32 v9, 31, v8
	v_lshlrev_b64 v[8:9], 12, v[8:9]
	v_lshl_add_u64 v[8:9], v[4:5], 0, v[8:9]
	global_load_dword v60, v[8:9], off
	v_add_u32_e32 v6, 8, v6
	v_add_u32_e32 v8, s8, v6
	v_ashrrev_i32_e32 v9, 31, v8
	v_lshlrev_b64 v[8:9], 12, v[8:9]
	v_lshl_add_u64 v[8:9], v[4:5], 0, v[8:9]
	global_load_dword v61, v[8:9], off
	v_add_u32_e32 v6, 8, v6
	v_add_u32_e32 v8, s8, v6
	v_ashrrev_i32_e32 v9, 31, v8
	v_lshlrev_b64 v[8:9], 12, v[8:9]
	v_lshl_add_u64 v[8:9], v[4:5], 0, v[8:9]
	global_load_dword v62, v[8:9], off
	v_add_u32_e32 v6, 8, v6
	v_add_u32_e32 v8, s8, v6
	v_ashrrev_i32_e32 v9, 31, v8
	v_lshlrev_b64 v[8:9], 12, v[8:9]
	v_lshl_add_u64 v[8:9], v[4:5], 0, v[8:9]
	global_load_dword v63, v[8:9], off
	v_add_u32_e32 v6, 8, v6
	s_or_b64 exec, exec, s[4:5]
	v_ashrrev_i32_e32 v6, 6, v1
	v_mad_u64_u32 v[8:9], s[4:5], v6, s14, v[2:3]
	v_mov_b32_e32 v64, v8
	v_add_u32_e32 v6, 8, v6
	v_mad_u64_u32 v[8:9], s[4:5], v6, s14, v[2:3]
	v_mov_b32_e32 v65, v8
	v_add_u32_e32 v6, 8, v6
	v_mad_u64_u32 v[8:9], s[4:5], v6, s14, v[2:3]
	v_mov_b32_e32 v66, v8
	v_add_u32_e32 v6, 8, v6
	v_mad_u64_u32 v[8:9], s[4:5], v6, s14, v[2:3]
	v_mov_b32_e32 v67, v8
	v_add_u32_e32 v6, 8, v6
	v_mad_u64_u32 v[8:9], s[4:5], v6, s14, v[2:3]
	v_mov_b32_e32 v68, v8
	v_add_u32_e32 v6, 8, v6
	v_mad_u64_u32 v[8:9], s[4:5], v6, s14, v[2:3]
	v_mov_b32_e32 v69, v8
	v_add_u32_e32 v6, 8, v6
	v_mad_u64_u32 v[8:9], s[4:5], v6, s14, v[2:3]
	v_mov_b32_e32 v70, v8
	v_add_u32_e32 v6, 8, v6
	v_mad_u64_u32 v[8:9], s[4:5], v6, s14, v[2:3]
	v_mov_b32_e32 v71, v8
	v_add_u32_e32 v6, 8, v6
	s_waitcnt vmcnt(7)
	ds_write_b32 v64, v56
	s_waitcnt vmcnt(6)
	ds_write_b32 v65, v57
	s_waitcnt vmcnt(5)
	ds_write_b32 v66, v58
	s_waitcnt vmcnt(4)
	ds_write_b32 v67, v59
	s_waitcnt vmcnt(3)
	ds_write_b32 v68, v60
	s_waitcnt vmcnt(2)
	ds_write_b32 v69, v61
	s_waitcnt vmcnt(1)
	ds_write_b32 v70, v62
	s_waitcnt vmcnt(0)
	ds_write_b32 v71, v63

; DI int otid() { int t = __builtin_amdgcn_workitem_id_x(); asm volatile("" : "+v"(t)); return t; }
; DI u16 f2bf(float x) { return (u16)(pack2(x, 0.f) & 0xffffu); }
; DI void transpose_w(const float* __restrict__ src, u16* __restrict__ dst, int N, int Npad, float* tl) {
;     ...
;   for (int t = blockIdx.x; t < ntiles; t += gridDim.x) {
;     const int kt = t / ntn, nt = t - kt * ntn, k0 = kt * 64, n0 = nt * 64;
;     for (int e = otid(); e < 4096; e += 512) { int r = e >> 6, c = e & 63, n = n0 + c; tl[r * 65 + c] = (n < N) ? src[(size_t)(k0 + r) * N + n] : 0.f; }
;     __syncthreads();
;     for (int e = otid(); e < 4096; e += 512) { int r = e >> 6, c = e & 63; dst[(size_t)(n0 + r) * 1024 + k0 + c] = f2bf(tl[c * 65 + r]); }
;     __syncthreads();
.LBB0_56:
	s_ashr_i32 s4, s17, 31
	s_lshr_b32 s4, s4, 28
	s_add_i32 s4, s17, s4
	s_ashr_i32 s4, s4, 4
	s_lshl_b32 s8, s4, 6
	s_lshl_b32 s4, s4, 10
	s_lshl_b32 s5, s17, 6
	v_mov_b32_e32 v1, v222
	s_sub_i32 s18, s5, s4
	s_nop 0
	v_cmp_gt_i32_e32 vcc, s2, v1
	s_and_saveexec_b64 s[10:11], vcc
	s_cbranch_execz .LBB0_61
	v_and_b32_e32 v2, 63, v1
	v_or_b32_e32 v4, s18, v2
	v_ashrrev_i32_e32 v5, 31, v4
	v_cmp_gt_i32_e32 vcc, s3, v4
	v_lshl_add_u64 v[4:5], v[4:5], 2, s[48:49]
	v_lshl_add_u32 v2, v2, 2, 0
	s_mov_b64 s[12:13], 0
	v_ashrrev_i32_e32 v6, 6, v1
	v_mov_b32_e32 v56, 0
	v_mov_b32_e32 v57, 0
	v_mov_b32_e32 v58, 0
	v_mov_b32_e32 v59, 0
	v_mov_b32_e32 v60, 0
	v_mov_b32_e32 v61, 0
	v_mov_b32_e32 v62, 0
	v_mov_b32_e32 v63, 0
	s_and_saveexec_b64 s[4:5], vcc
	v_add_u32_e32 v8, s8, v6
	v_ashrrev_i32_e32 v9, 31, v8
	v_lshlrev_b64 v[8:9], 12, v[8:9]
	v_lshl_add_u64 v[8:9], v[4:5], 0, v[8:9]
	global_load_dword v56, v[8:9], off
	v_add_u32_e32 v6, 8, v6
	v_add_u32_e32 v8, s8, v6
	v_ashrrev_i32_e32 v9, 31, v8
	v_lshlrev_b64 v[8:9], 12, v[8:9]
	v_lshl_add_u64 v[8:9], v[4:5], 0, v[8:9]
	global_load_dword v57, v[8:9], off
	v_add_u32_e32 v6, 8, v6
	v_add_u32_e32 v8, s8, v6
	v_ashrrev_i32_e32 v9, 31, v8
	v_lshlrev_b64 v[8:9], 12, v[8:9]
	v_lshl_add_u64 v[8:9], v[4:5], 0, v[8:9]
	global_load_dword v58, v[8:9], off
	v_add_u32_e32 v6, 8, v6
	v_add_u32_e32 v8, s8, v6
	v_ashrrev_i32_e32 v9, 31, v8
	v_lshlrev_b64 v[8:9], 12, v[8:9]
	v_lshl_add_u64 v[8:9], v[4:5], 0, v[8:9]
	global_load_dword v59, v[8:9], off
	v_add_u32_e32 v6, 8, v6
	v_add_u32_e32 v8, s8, v6
	v_ashrrev_i32_e32 v9, 31, v8
	v_lshlrev_b64 v[8:9], 12, v[8:9]
	v_lshl_add_u64 v[8:9], v[4:5], 0, v[8:9]
	global_load_dword v60, v[8:9], off
	v_add_u32_e32 v6, 8, v6
	v_add_u32_e32 v8, s8, v6
	v_ashrrev_i32_e32 v9, 31, v8
	v_lshlrev_b64 v[8:9], 12, v[8:9]
	v_lshl_add_u64 v[8:9], v[4:5], 0, v[8:9]
	global_load_dword v61, v[8:9], off
	v_add_u32_e32 v6, 8, v6
	v_add_u32_e32 v8, s8, v6
	v_ashrrev_i32_e32 v9, 31, v8
	v_lshlrev_b64 v[8:9], 12, v[8:9]
	v_lshl_add_u64 v[8:9], v[4:5], 0, v[8:9]
	global_load_dword v62, v[8:9], off
	v_add_u32_e32 v6, 8, v6
	v_add_u32_e32 v8, s8, v6
	v_ashrrev_i32_e32 v9, 31, v8
	v_lshlrev_b64 v[8:9], 12, v[8:9]
	v_lshl_add_u64 v[8:9], v[4:5], 0, v[8:9]
	global_load_dword v63, v[8:9], off
	v_add_u32_e32 v6, 8, v6
	s_or_b64 exec, exec, s[4:5]
	v_ashrrev_i32_e32 v6, 6, v1
	v_mad_u64_u32 v[8:9], s[4:5], v6, s14, v[2:3]
	v_mov_b32_e32 v64, v8
	v_add_u32_e32 v6, 8, v6
	v_mad_u64_u32 v[8:9], s[4:5], v6, s14, v[2:3]
	v_mov_b32_e32 v65, v8
	v_add_u32_e32 v6, 8, v6
	v_mad_u64_u32 v[8:9], s[4:5], v6, s14, v[2:3]
	v_mov_b32_e32 v66, v8
	v_add_u32_e32 v6, 8, v6
	v_mad_u64_u32 v[8:9], s[4:5], v6, s14, v[2:3]
	v_mov_b32_e32 v67, v8
	v_add_u32_e32 v6, 8, v6
	v_mad_u64_u32 v[8:9], s[4:5], v6, s14, v[2:3]
	v_mov_b32_e32 v68, v8
	v_add_u32_e32 v6, 8, v6
	v_mad_u64_u32 v[8:9], s[4:5], v6, s14, v[2:3]
	v_mov_b32_e32 v69, v8
	v_add_u32_e32 v6, 8, v6
	v_mad_u64_u32 v[8:9], s[4:5], v6, s14, v[2:3]
	v_mov_b32_e32 v70, v8
	v_add_u32_e32 v6, 8, v6
	v_mad_u64_u32 v[8:9], s[4:5], v6, s14, v[2:3]
	v_mov_b32_e32 v71, v8
	v_add_u32_e32 v6, 8, v6
	s_waitcnt vmcnt(7)
	ds_write_b32 v64, v56
	s_waitcnt vmcnt(6)
	ds_write_b32 v65, v57
	s_waitcnt vmcnt(5)
	ds_write_b32 v66, v58
	s_waitcnt vmcnt(4)
	ds_write_b32 v67, v59
	s_waitcnt vmcnt(3)
	ds_write_b32 v68, v60
	s_waitcnt vmcnt(2)
	ds_write_b32 v69, v61
	s_waitcnt vmcnt(1)
	ds_write_b32 v70, v62
	s_waitcnt vmcnt(0)
	ds_write_b32 v71, v63

; DI int otid() { int t = __builtin_amdgcn_workitem_id_x(); asm volatile("" : "+v"(t)); return t; }
; DI u16 f2bf(float x) { return (u16)(pack2(x, 0.f) & 0xffffu); }
; DI void transpose_w(const float* __restrict__ src, u16* __restrict__ dst, int N, int Npad, float* tl) {
;     ...
;   for (int t = blockIdx.x; t < ntiles; t += gridDim.x) {
;     const int kt = t / ntn, nt = t - kt * ntn, k0 = kt * 64, n0 = nt * 64;
;     for (int e = otid(); e < 4096; e += 512) { int r = e >> 6, c = e & 63, n = n0 + c; tl[r * 65 + c] = (n < N) ? src[(size_t)(k0 + r) * N + n] : 0.f; }
;     __syncthreads();
;     for (int e = otid(); e < 4096; e += 512) { int r = e >> 6, c = e & 63; dst[(size_t)(n0 + r) * 1024 + k0 + c] = f2bf(tl[c * 65 + r]); }
;     __syncthreads();
.LBB0_77:
	s_ashr_i32 s4, s19, 31
	s_lshr_b32 s4, s4, 27
	s_add_i32 s4, s19, s4
	s_ashr_i32 s4, s4, 5
	s_lshl_b32 s8, s4, 6
	s_lshl_b32 s4, s4, 11
	s_lshl_b32 s5, s19, 6
	v_mov_b32_e32 v1, v222
	s_sub_i32 s20, s5, s4
	s_nop 0
	v_cmp_gt_i32_e32 vcc, s3, v1
	s_and_saveexec_b64 s[12:13], vcc
	s_cbranch_execz .LBB0_82
	v_and_b32_e32 v2, 63, v1
	v_or_b32_e32 v4, s20, v2
	v_ashrrev_i32_e32 v5, 31, v4
	v_cmp_gt_i32_e32 vcc, s16, v4
	s_waitcnt lgkmcnt(0)
	v_lshl_add_u64 v[4:5], v[4:5], 2, s[50:51]
	v_lshl_add_u32 v2, v2, 2, 0
	s_mov_b64 s[14:15], 0
	v_ashrrev_i32_e32 v6, 6, v1
	v_mov_b32_e32 v56, 0
	v_mov_b32_e32 v57, 0
	v_mov_b32_e32 v58, 0
	v_mov_b32_e32 v59, 0
	v_mov_b32_e32 v60, 0
	v_mov_b32_e32 v61, 0
	v_mov_b32_e32 v62, 0
	v_mov_b32_e32 v63, 0
	s_and_saveexec_b64 s[4:5], vcc
	v_add_u32_e32 v8, s8, v6
	v_ashrrev_i32_e32 v9, 31, v8
	v_lshlrev_b64 v[8:9], 13, v[8:9]
	v_lshl_add_u64 v[8:9], v[4:5], 0, v[8:9]
	global_load_dword v56, v[8:9], off
	v_add_u32_e32 v6, 8, v6
	v_add_u32_e32 v8, s8, v6
	v_ashrrev_i32_e32 v9, 31, v8
	v_lshlrev_b64 v[8:9], 13, v[8:9]
	v_lshl_add_u64 v[8:9], v[4:5], 0, v[8:9]
	global_load_dword v57, v[8:9], off
	v_add_u32_e32 v6, 8, v6
	v_add_u32_e32 v8, s8, v6
	v_ashrrev_i32_e32 v9, 31, v8
	v_lshlrev_b64 v[8:9], 13, v[8:9]
	v_lshl_add_u64 v[8:9], v[4:5], 0, v[8:9]
	global_load_dword v58, v[8:9], off
	v_add_u32_e32 v6, 8, v6
	v_add_u32_e32 v8, s8, v6
	v_ashrrev_i32_e32 v9, 31, v8
	v_lshlrev_b64 v[8:9], 13, v[8:9]
	v_lshl_add_u64 v[8:9], v[4:5], 0, v[8:9]
	global_load_dword v59, v[8:9], off
	v_add_u32_e32 v6, 8, v6
	v_add_u32_e32 v8, s8, v6
	v_ashrrev_i32_e32 v9, 31, v8
	v_lshlrev_b64 v[8:9], 13, v[8:9]
	v_lshl_add_u64 v[8:9], v[4:5], 0, v[8:9]
	global_load_dword v60, v[8:9], off
	v_add_u32_e32 v6, 8, v6
	v_add_u32_e32 v8, s8, v6
	v_ashrrev_i32_e32 v9, 31, v8
	v_lshlrev_b64 v[8:9], 13, v[8:9]
	v_lshl_add_u64 v[8:9], v[4:5], 0, v[8:9]
	global_load_dword v61, v[8:9], off
	v_add_u32_e32 v6, 8, v6
	v_add_u32_e32 v8, s8, v6
	v_ashrrev_i32_e32 v9, 31, v8
	v_lshlrev_b64 v[8:9], 13, v[8:9]
	v_lshl_add_u64 v[8:9], v[4:5], 0, v[8:9]
	global_load_dword v62, v[8:9], off
	v_add_u32_e32 v6, 8, v6
	v_add_u32_e32 v8, s8, v6
	v_ashrrev_i32_e32 v9, 31, v8
	v_lshlrev_b64 v[8:9], 13, v[8:9]
	v_lshl_add_u64 v[8:9], v[4:5], 0, v[8:9]
	global_load_dword v63, v[8:9], off
	v_add_u32_e32 v6, 8, v6
	s_or_b64 exec, exec, s[4:5]
	v_ashrrev_i32_e32 v6, 6, v1
	v_mad_u64_u32 v[8:9], s[4:5], v6, s17, v[2:3]
	v_mov_b32_e32 v64, v8
	v_add_u32_e32 v6, 8, v6
	v_mad_u64_u32 v[8:9], s[4:5], v6, s17, v[2:3]
	v_mov_b32_e32 v65, v8
	v_add_u32_e32 v6, 8, v6
	v_mad_u64_u32 v[8:9], s[4:5], v6, s17, v[2:3]
	v_mov_b32_e32 v66, v8
	v_add_u32_e32 v6, 8, v6
	v_mad_u64_u32 v[8:9], s[4:5], v6, s17, v[2:3]
	v_mov_b32_e32 v67, v8
	v_add_u32_e32 v6, 8, v6
	v_mad_u64_u32 v[8:9], s[4:5], v6, s17, v[2:3]
	v_mov_b32_e32 v68, v8
	v_add_u32_e32 v6, 8, v6
	v_mad_u64_u32 v[8:9], s[4:5], v6, s17, v[2:3]
	v_mov_b32_e32 v69, v8
	v_add_u32_e32 v6, 8, v6
	v_mad_u64_u32 v[8:9], s[4:5], v6, s17, v[2:3]
	v_mov_b32_e32 v70, v8
	v_add_u32_e32 v6, 8, v6
	v_mad_u64_u32 v[8:9], s[4:5], v6, s17, v[2:3]
	v_mov_b32_e32 v71, v8
	v_add_u32_e32 v6, 8, v6
	s_waitcnt vmcnt(7)
	ds_write_b32 v64, v56
	s_waitcnt vmcnt(6)
	ds_write_b32 v65, v57
	s_waitcnt vmcnt(5)
	ds_write_b32 v66, v58
	s_waitcnt vmcnt(4)
	ds_write_b32 v67, v59
	s_waitcnt vmcnt(3)
	ds_write_b32 v68, v60
	s_waitcnt vmcnt(2)
	ds_write_b32 v69, v61
	s_waitcnt vmcnt(1)
	ds_write_b32 v70, v62
	s_waitcnt vmcnt(0)
	ds_write_b32 v71, v63

; DI int otid() { int t = __builtin_amdgcn_workitem_id_x(); asm volatile("" : "+v"(t)); return t; }
; DI u16 f2bf(float x) { return (u16)(pack2(x, 0.f) & 0xffffu); }
; DI void transpose_w(const float* __restrict__ src, u16* __restrict__ dst, int N, int Npad, float* tl) {
;     ...
;   for (int t = blockIdx.x; t < ntiles; t += gridDim.x) {
;     const int kt = t / ntn, nt = t - kt * ntn, k0 = kt * 64, n0 = nt * 64;
;     for (int e = otid(); e < 4096; e += 512) { int r = e >> 6, c = e & 63, n = n0 + c; tl[r * 65 + c] = (n < N) ? src[(size_t)(k0 + r) * N + n] : 0.f; }
;     __syncthreads();
;     for (int e = otid(); e < 4096; e += 512) { int r = e >> 6, c = e & 63; dst[(size_t)(n0 + r) * 1024 + k0 + c] = f2bf(tl[c * 65 + r]); }
;     __syncthreads();
.LBB0_98:
	s_ashr_i32 s4, s17, 31
	s_lshr_b32 s4, s4, 28
	s_add_i32 s4, s17, s4
	s_ashr_i32 s4, s4, 4
	s_lshl_b32 s6, s4, 6
	s_lshl_b32 s4, s4, 10
	s_lshl_b32 s5, s17, 6
	v_mov_b32_e32 v1, v222
	s_sub_i32 s18, s5, s4
	s_nop 0
	v_cmp_gt_i32_e32 vcc, s2, v1
	s_and_saveexec_b64 s[4:5], vcc
	s_cbranch_execz .LBB0_103
	s_load_dwordx16 s[72:87], s[0:1], 0x80
	v_and_b32_e32 v2, 63, v1
	v_or_b32_e32 v4, s18, v2
	v_ashrrev_i32_e32 v5, 31, v4
	v_cmp_gt_i32_e32 vcc, s3, v4
	s_waitcnt lgkmcnt(0)
	v_lshl_add_u64 v[4:5], v[4:5], 2, s[72:73]
	v_lshl_add_u32 v2, v2, 2, 0
	s_mov_b64 s[12:13], 0
	v_ashrrev_i32_e32 v6, 6, v1
	v_mov_b32_e32 v56, 0
	v_mov_b32_e32 v57, 0
	v_mov_b32_e32 v58, 0
	v_mov_b32_e32 v59, 0
	v_mov_b32_e32 v60, 0
	v_mov_b32_e32 v61, 0
	v_mov_b32_e32 v62, 0
	v_mov_b32_e32 v63, 0
	s_and_saveexec_b64 s[8:9], vcc
	v_add_u32_e32 v8, s6, v6
	v_ashrrev_i32_e32 v9, 31, v8
	v_lshlrev_b64 v[8:9], 12, v[8:9]
	v_lshl_add_u64 v[8:9], v[4:5], 0, v[8:9]
	global_load_dword v56, v[8:9], off
	v_add_u32_e32 v6, 8, v6
	v_add_u32_e32 v8, s6, v6
	v_ashrrev_i32_e32 v9, 31, v8
	v_lshlrev_b64 v[8:9], 12, v[8:9]
	v_lshl_add_u64 v[8:9], v[4:5], 0, v[8:9]
	global_load_dword v57, v[8:9], off
	v_add_u32_e32 v6, 8, v6
	v_add_u32_e32 v8, s6, v6
	v_ashrrev_i32_e32 v9, 31, v8
	v_lshlrev_b64 v[8:9], 12, v[8:9]
	v_lshl_add_u64 v[8:9], v[4:5], 0, v[8:9]
	global_load_dword v58, v[8:9], off
	v_add_u32_e32 v6, 8, v6
	v_add_u32_e32 v8, s6, v6
	v_ashrrev_i32_e32 v9, 31, v8
	v_lshlrev_b64 v[8:9], 12, v[8:9]
	v_lshl_add_u64 v[8:9], v[4:5], 0, v[8:9]
	global_load_dword v59, v[8:9], off
	v_add_u32_e32 v6, 8, v6
	v_add_u32_e32 v8, s6, v6
	v_ashrrev_i32_e32 v9, 31, v8
	v_lshlrev_b64 v[8:9], 12, v[8:9]
	v_lshl_add_u64 v[8:9], v[4:5], 0, v[8:9]
	global_load_dword v60, v[8:9], off
	v_add_u32_e32 v6, 8, v6
	v_add_u32_e32 v8, s6, v6
	v_ashrrev_i32_e32 v9, 31, v8
	v_lshlrev_b64 v[8:9], 12, v[8:9]
	v_lshl_add_u64 v[8:9], v[4:5], 0, v[8:9]
	global_load_dword v61, v[8:9], off
	v_add_u32_e32 v6, 8, v6
	v_add_u32_e32 v8, s6, v6
	v_ashrrev_i32_e32 v9, 31, v8
	v_lshlrev_b64 v[8:9], 12, v[8:9]
	v_lshl_add_u64 v[8:9], v[4:5], 0, v[8:9]
	global_load_dword v62, v[8:9], off
	v_add_u32_e32 v6, 8, v6
	v_add_u32_e32 v8, s6, v6
	v_ashrrev_i32_e32 v9, 31, v8
	v_lshlrev_b64 v[8:9], 12, v[8:9]
	v_lshl_add_u64 v[8:9], v[4:5], 0, v[8:9]
	global_load_dword v63, v[8:9], off
	v_add_u32_e32 v6, 8, v6
	s_or_b64 exec, exec, s[8:9]
	v_ashrrev_i32_e32 v6, 6, v1
	v_mad_u64_u32 v[8:9], s[8:9], v6, s14, v[2:3]
	v_mov_b32_e32 v64, v8
	v_add_u32_e32 v6, 8, v6
	v_mad_u64_u32 v[8:9], s[8:9], v6, s14, v[2:3]
	v_mov_b32_e32 v65, v8
	v_add_u32_e32 v6, 8, v6
	v_mad_u64_u32 v[8:9], s[8:9], v6, s14, v[2:3]
	v_mov_b32_e32 v66, v8
	v_add_u32_e32 v6, 8, v6
	v_mad_u64_u32 v[8:9], s[8:9], v6, s14, v[2:3]
	v_mov_b32_e32 v67, v8
	v_add_u32_e32 v6, 8, v6
	v_mad_u64_u32 v[8:9], s[8:9], v6, s14, v[2:3]
	v_mov_b32_e32 v68, v8
	v_add_u32_e32 v6, 8, v6
	v_mad_u64_u32 v[8:9], s[8:9], v6, s14, v[2:3]
	v_mov_b32_e32 v69, v8
	v_add_u32_e32 v6, 8, v6
	v_mad_u64_u32 v[8:9], s[8:9], v6, s14, v[2:3]
	v_mov_b32_e32 v70, v8
	v_add_u32_e32 v6, 8, v6
	v_mad_u64_u32 v[8:9], s[8:9], v6, s14, v[2:3]
	v_mov_b32_e32 v71, v8
	v_add_u32_e32 v6, 8, v6
	s_waitcnt vmcnt(7)
	ds_write_b32 v64, v56
	s_waitcnt vmcnt(6)
	ds_write_b32 v65, v57
	s_waitcnt vmcnt(5)
	ds_write_b32 v66, v58
	s_waitcnt vmcnt(4)
	ds_write_b32 v67, v59
	s_waitcnt vmcnt(3)
	ds_write_b32 v68, v60
	s_waitcnt vmcnt(2)
	ds_write_b32 v69, v61
	s_waitcnt vmcnt(1)
	ds_write_b32 v70, v62
	s_waitcnt vmcnt(0)
	ds_write_b32 v71, v63

; DI int otid() { int t = __builtin_amdgcn_workitem_id_x(); asm volatile("" : "+v"(t)); return t; }
; DI u16 f2bf(float x) { return (u16)(pack2(x, 0.f) & 0xffffu); }
; DI void transpose_w(const float* __restrict__ src, u16* __restrict__ dst, int N, int Npad, float* tl) {
;     ...
;   for (int t = blockIdx.x; t < ntiles; t += gridDim.x) {
;     const int kt = t / ntn, nt = t - kt * ntn, k0 = kt * 64, n0 = nt * 64;
;     for (int e = otid(); e < 4096; e += 512) { int r = e >> 6, c = e & 63, n = n0 + c; tl[r * 65 + c] = (n < N) ? src[(size_t)(k0 + r) * N + n] : 0.f; }
;     __syncthreads();
;     for (int e = otid(); e < 4096; e += 512) { int r = e >> 6, c = e & 63; dst[(size_t)(n0 + r) * 1024 + k0 + c] = f2bf(tl[c * 65 + r]); }
;     __syncthreads();
.LBB0_119:
	s_ashr_i32 s0, s13, 31
	s_lshr_b32 s0, s0, 27
	s_add_i32 s0, s13, s0
	s_ashr_i32 s0, s0, 5
	s_lshl_b32 s4, s0, 6
	s_lshl_b32 s0, s0, 11
	s_lshl_b32 s1, s13, 6
	v_mov_b32_e32 v1, v222
	s_sub_i32 s14, s1, s0
	s_nop 0
	v_cmp_gt_i32_e32 vcc, s2, v1
	s_and_saveexec_b64 s[6:7], vcc
	s_cbranch_execz .LBB0_124
	v_and_b32_e32 v2, 63, v1
	v_or_b32_e32 v4, s14, v2
	v_readlane_b32 s16, v250, 30
	v_ashrrev_i32_e32 v5, 31, v4
	v_readlane_b32 s22, v250, 36
	v_readlane_b32 s23, v250, 37
	v_cmp_gt_i32_e32 vcc, s3, v4
	v_lshl_add_u32 v2, v2, 2, 0
	v_lshl_add_u64 v[4:5], v[4:5], 2, s[22:23]
	s_mov_b64 s[8:9], 0
	v_readlane_b32 s17, v250, 31
	v_readlane_b32 s18, v250, 32
	v_readlane_b32 s19, v250, 33
	v_readlane_b32 s20, v250, 34
	v_readlane_b32 s21, v250, 35
	v_readlane_b32 s24, v250, 38
	v_readlane_b32 s25, v250, 39
	v_readlane_b32 s26, v250, 40
	v_readlane_b32 s27, v250, 41
	v_readlane_b32 s28, v250, 42
	v_readlane_b32 s29, v250, 43
	v_readlane_b32 s30, v250, 44
	v_readlane_b32 s31, v250, 45
	v_ashrrev_i32_e32 v6, 6, v1
	v_mov_b32_e32 v56, 0
	v_mov_b32_e32 v57, 0
	v_mov_b32_e32 v58, 0
	v_mov_b32_e32 v59, 0
	v_mov_b32_e32 v60, 0
	v_mov_b32_e32 v61, 0
	v_mov_b32_e32 v62, 0
	v_mov_b32_e32 v63, 0
	s_and_saveexec_b64 s[0:1], vcc
	v_add_u32_e32 v8, s4, v6
	v_ashrrev_i32_e32 v9, 31, v8
	v_lshlrev_b64 v[8:9], 13, v[8:9]
	v_lshl_add_u64 v[8:9], v[4:5], 0, v[8:9]
	global_load_dword v56, v[8:9], off
	v_add_u32_e32 v6, 8, v6
	v_add_u32_e32 v8, s4, v6
	v_ashrrev_i32_e32 v9, 31, v8
	v_lshlrev_b64 v[8:9], 13, v[8:9]
	v_lshl_add_u64 v[8:9], v[4:5], 0, v[8:9]
	global_load_dword v57, v[8:9], off
	v_add_u32_e32 v6, 8, v6
	v_add_u32_e32 v8, s4, v6
	v_ashrrev_i32_e32 v9, 31, v8
	v_lshlrev_b64 v[8:9], 13, v[8:9]
	v_lshl_add_u64 v[8:9], v[4:5], 0, v[8:9]
	global_load_dword v58, v[8:9], off
	v_add_u32_e32 v6, 8, v6
	v_add_u32_e32 v8, s4, v6
	v_ashrrev_i32_e32 v9, 31, v8
	v_lshlrev_b64 v[8:9], 13, v[8:9]
	v_lshl_add_u64 v[8:9], v[4:5], 0, v[8:9]
	global_load_dword v59, v[8:9], off
	v_add_u32_e32 v6, 8, v6
	v_add_u32_e32 v8, s4, v6
	v_ashrrev_i32_e32 v9, 31, v8
	v_lshlrev_b64 v[8:9], 13, v[8:9]
	v_lshl_add_u64 v[8:9], v[4:5], 0, v[8:9]
	global_load_dword v60, v[8:9], off
	v_add_u32_e32 v6, 8, v6
	v_add_u32_e32 v8, s4, v6
	v_ashrrev_i32_e32 v9, 31, v8
	v_lshlrev_b64 v[8:9], 13, v[8:9]
	v_lshl_add_u64 v[8:9], v[4:5], 0, v[8:9]
	global_load_dword v61, v[8:9], off
	v_add_u32_e32 v6, 8, v6
	v_add_u32_e32 v8, s4, v6
	v_ashrrev_i32_e32 v9, 31, v8
	v_lshlrev_b64 v[8:9], 13, v[8:9]
	v_lshl_add_u64 v[8:9], v[4:5], 0, v[8:9]
	global_load_dword v62, v[8:9], off
	v_add_u32_e32 v6, 8, v6
	v_add_u32_e32 v8, s4, v6
	v_ashrrev_i32_e32 v9, 31, v8
	v_lshlrev_b64 v[8:9], 13, v[8:9]
	v_lshl_add_u64 v[8:9], v[4:5], 0, v[8:9]
	global_load_dword v63, v[8:9], off
	v_add_u32_e32 v6, 8, v6
	s_or_b64 exec, exec, s[0:1]
	v_ashrrev_i32_e32 v6, 6, v1
	v_mad_u64_u32 v[8:9], s[0:1], v6, s10, v[2:3]
	v_mov_b32_e32 v64, v8
	v_add_u32_e32 v6, 8, v6
	v_mad_u64_u32 v[8:9], s[0:1], v6, s10, v[2:3]
	v_mov_b32_e32 v65, v8
	v_add_u32_e32 v6, 8, v6
	v_mad_u64_u32 v[8:9], s[0:1], v6, s10, v[2:3]
	v_mov_b32_e32 v66, v8
	v_add_u32_e32 v6, 8, v6
	v_mad_u64_u32 v[8:9], s[0:1], v6, s10, v[2:3]
	v_mov_b32_e32 v67, v8
	v_add_u32_e32 v6, 8, v6
	v_mad_u64_u32 v[8:9], s[0:1], v6, s10, v[2:3]
	v_mov_b32_e32 v68, v8
	v_add_u32_e32 v6, 8, v6
	v_mad_u64_u32 v[8:9], s[0:1], v6, s10, v[2:3]
	v_mov_b32_e32 v69, v8
	v_add_u32_e32 v6, 8, v6
	v_mad_u64_u32 v[8:9], s[0:1], v6, s10, v[2:3]
	v_mov_b32_e32 v70, v8
	v_add_u32_e32 v6, 8, v6
	v_mad_u64_u32 v[8:9], s[0:1], v6, s10, v[2:3]
	v_mov_b32_e32 v71, v8
	v_add_u32_e32 v6, 8, v6
	s_waitcnt vmcnt(7)
	ds_write_b32 v64, v56
	s_waitcnt vmcnt(6)
	ds_write_b32 v65, v57
	s_waitcnt vmcnt(5)
	ds_write_b32 v66, v58
	s_waitcnt vmcnt(4)
	ds_write_b32 v67, v59
	s_waitcnt vmcnt(3)
	ds_write_b32 v68, v60
	s_waitcnt vmcnt(2)
	ds_write_b32 v69, v61
	s_waitcnt vmcnt(1)
	ds_write_b32 v70, v62
	s_waitcnt vmcnt(0)
	ds_write_b32 v71, v63
